# DSA attention: per-query z-gate row load issued at the start of the PV phase instead of after it
# baseline (speedup 1.0000x reference)
; __device__ __forceinline__ void dsa_wave(const Params& p, int rank, char* sm) {
;     ...
;     const bool b5 = (lane >> 5) & 1, b4 = (lane >> 4) & 1, b3 = (lane >> 3) & 1;
;     float o32[32], o16[16], o8[8];
; #pragma unroll
;     for (int i = 0; i < 32; i++) { float lo = o[i], hi = o[32 + i]; float snd = b5 ? lo : hi; float kp = b5 ? hi : lo; o32[i] = kp + __shfl_xor(snd, 32); }
; #pragma unroll
;     for (int i = 0; i < 16; i++) { float lo = o32[i], hi = o32[16 + i]; float snd = b4 ? lo : hi; float kp = b4 ? hi : lo; o16[i] = kp + __shfl_xor(snd, 16); }
; #pragma unroll
;     for (int i = 0; i < 8; i++) { float lo = o16[i], hi = o16[8 + i]; float snd = b3 ? lo : hi; float kp = b3 ? hi : lo; o8[i] = kp + __shfl_xor(snd, 8); }
;     const float s_g0 = b4 ? (b3 ? ssum[0][3] : ssum[0][2]) : (b3 ? ssum[0][1] : ssum[0][0]);
;     const float s_g1 = b4 ? (b3 ? ssum[1][3] : ssum[1][2]) : (b3 ? ssum[1][1] : ssum[1][0]);
;     const float rinv = 1.f / (b5 ? s_g1 : s_g0);
.LBB0_1493:
	v_and_b32_e32 v1, 64, v202
	v_xor_b32_e32 v0, 32, v202
	v_add_u32_e32 v1, 64, v1
	v_cmp_lt_i32_e32 vcc, v0, v1
	v_cndmask_b32_e64 v2, v114, v164, s[12:13]
	v_mov_b32_e32 v3, s2
	v_cndmask_b32_e32 v0, v202, v0, vcc
	v_lshlrev_b32_e32 v0, 2, v0
	ds_bpermute_b32 v56, v0, v2
	v_cndmask_b32_e64 v2, v115, v165, s[12:13]
	ds_bpermute_b32 v57, v0, v2
	v_cndmask_b32_e64 v2, v112, v162, s[12:13]
	ds_bpermute_b32 v40, v0, v2
	v_cndmask_b32_e64 v2, v113, v163, s[12:13]
	ds_bpermute_b32 v41, v0, v2
	v_cndmask_b32_e64 v2, v110, v160, s[12:13]
	ds_bpermute_b32 v24, v0, v2
	v_cndmask_b32_e64 v2, v111, v161, s[12:13]
	ds_bpermute_b32 v25, v0, v2
	v_cndmask_b32_e64 v2, v108, v158, s[12:13]
	ds_bpermute_b32 v6, v0, v2
	v_cndmask_b32_e64 v2, v109, v159, s[12:13]
	ds_bpermute_b32 v7, v0, v2
	v_cndmask_b32_e64 v2, v106, v156, s[12:13]
	ds_bpermute_b32 v60, v0, v2
	v_cndmask_b32_e64 v2, v107, v157, s[12:13]
	ds_bpermute_b32 v61, v0, v2
	v_cndmask_b32_e64 v2, v104, v154, s[12:13]
	ds_bpermute_b32 v44, v0, v2
	v_cndmask_b32_e64 v2, v105, v155, s[12:13]
	ds_bpermute_b32 v45, v0, v2
	v_cndmask_b32_e64 v2, v102, v134, s[12:13]
	ds_bpermute_b32 v28, v0, v2
	v_cndmask_b32_e64 v2, v103, v135, s[12:13]
	ds_bpermute_b32 v29, v0, v2
	v_cndmask_b32_e64 v2, v100, v132, s[12:13]
	ds_bpermute_b32 v12, v0, v2
	v_cndmask_b32_e64 v2, v101, v133, s[12:13]
	ds_bpermute_b32 v13, v0, v2
	v_cndmask_b32_e64 v2, v96, v128, s[12:13]
	ds_bpermute_b32 v64, v0, v2
	v_cndmask_b32_e64 v2, v97, v129, s[12:13]
	ds_bpermute_b32 v65, v0, v2
	v_cndmask_b32_e64 v2, v92, v124, s[12:13]
	ds_bpermute_b32 v48, v0, v2
	v_cndmask_b32_e64 v2, v93, v125, s[12:13]
	ds_bpermute_b32 v49, v0, v2
	v_cndmask_b32_e64 v2, v88, v120, s[12:13]
	ds_bpermute_b32 v32, v0, v2
	v_cndmask_b32_e64 v2, v89, v121, s[12:13]
	ds_bpermute_b32 v33, v0, v2
	v_cndmask_b32_e64 v2, v84, v116, s[12:13]
	ds_bpermute_b32 v16, v0, v2
	v_cndmask_b32_e64 v2, v85, v117, s[12:13]
	ds_bpermute_b32 v17, v0, v2
	v_cndmask_b32_e64 v2, v98, v130, s[12:13]
	ds_bpermute_b32 v68, v0, v2
	v_cndmask_b32_e64 v2, v99, v131, s[12:13]
	ds_bpermute_b32 v69, v0, v2
	v_cndmask_b32_e64 v2, v94, v126, s[12:13]
	ds_bpermute_b32 v52, v0, v2
	v_cndmask_b32_e64 v2, v95, v127, s[12:13]
	ds_bpermute_b32 v53, v0, v2
	v_cndmask_b32_e64 v2, v90, v122, s[12:13]
	ds_bpermute_b32 v36, v0, v2
	v_cndmask_b32_e64 v2, v91, v123, s[12:13]
	ds_bpermute_b32 v37, v0, v2
	v_cndmask_b32_e64 v2, v86, v118, s[12:13]
	ds_bpermute_b32 v20, v0, v2
	v_cndmask_b32_e64 v2, v87, v119, s[12:13]
	ds_bpermute_b32 v21, v0, v2
	v_xor_b32_e32 v0, 16, v202
	v_cmp_lt_i32_e32 vcc, v0, v1
	v_mov_b32_e32 v2, s85
	v_cndmask_b32_e64 v55, v165, v115, s[12:13]
	v_cndmask_b32_e32 v0, v202, v0, vcc
	v_lshlrev_b32_e32 v70, 2, v0
	v_xor_b32_e32 v0, 8, v202
	v_cmp_lt_i32_e32 vcc, v0, v1
	v_mov_b32_e32 v1, s87
	v_cndmask_b32_e64 v54, v164, v114, s[12:13]
	v_cndmask_b32_e32 v0, v202, v0, vcc
	v_lshlrev_b32_e32 v11, 2, v0
	v_mov_b32_e32 v0, s88
	v_cndmask_b32_e64 v0, v0, v1, s[10:11]
	v_mov_b32_e32 v1, s86
	v_cndmask_b32_e64 v1, v1, v2, s[10:11]
	v_cndmask_b32_e64 v0, v0, v1, s[8:9]
	v_mov_b32_e32 v1, s15
	v_mov_b32_e32 v2, s14
	v_cndmask_b32_e64 v1, v1, v2, s[10:11]
	v_mov_b32_e32 v2, s3
	v_cndmask_b32_e64 v2, v2, v3, s[10:11]
	v_cndmask_b32_e64 v1, v1, v2, s[8:9]
	v_cndmask_b32_e64 v0, v1, v0, s[12:13]
	v_div_scale_f32 v1, s[0:1], v0, v0, 1.0
	v_rcp_f32_e32 v2, v1
	v_cndmask_b32_e64 v59, v157, v107, s[12:13]
	v_cndmask_b32_e64 v58, v156, v106, s[12:13]
	v_cndmask_b32_e64 v63, v129, v97, s[12:13]
	v_fma_f32 v3, -v1, v2, 1.0
	v_fmac_f32_e32 v2, v3, v2
	v_div_scale_f32 v3, vcc, 1.0, v0, 1.0
	v_mul_f32_e32 v10, v3, v2
	v_fma_f32 v71, -v1, v10, v3
	v_fmac_f32_e32 v10, v71, v2
	v_fma_f32 v1, -v1, v10, v3
	v_div_fmas_f32 v1, v1, v2, v10
	v_div_fixup_f32 v10, v1, v0, 1.0
	v_cndmask_b32_e64 v62, v128, v96, s[12:13]
	s_waitcnt lgkmcnt(14)
	v_pk_add_f32 v[54:55], v[54:55], v[56:57]
	v_pk_add_f32 v[56:57], v[58:59], v[60:61]
	v_pk_add_f32 v[58:59], v[62:63], v[64:65]
	v_cndmask_b32_e64 v67, v131, v99, s[12:13]
	v_cndmask_b32_e64 v66, v130, v98, s[12:13]
	s_waitcnt lgkmcnt(6)
	v_pk_add_f32 v[60:61], v[66:67], v[68:69]
	v_cndmask_b32_e64 v39, v163, v113, s[12:13]
	v_cndmask_b32_e64 v38, v162, v112, s[12:13]
	v_cndmask_b32_e64 v43, v155, v105, s[12:13]
	v_cndmask_b32_e64 v42, v154, v104, s[12:13]
	v_cndmask_b32_e64 v47, v125, v93, s[12:13]
	v_cndmask_b32_e64 v46, v124, v92, s[12:13]
	v_pk_add_f32 v[38:39], v[38:39], v[40:41]
	v_pk_add_f32 v[40:41], v[42:43], v[44:45]
	v_pk_add_f32 v[42:43], v[46:47], v[48:49]
	v_cndmask_b32_e64 v51, v127, v95, s[12:13]
	v_cndmask_b32_e64 v50, v126, v94, s[12:13]
	s_waitcnt lgkmcnt(4)
	v_pk_add_f32 v[44:45], v[50:51], v[52:53]
	v_cndmask_b32_e64 v23, v161, v111, s[12:13]
	v_cndmask_b32_e64 v22, v160, v110, s[12:13]
	v_cndmask_b32_e64 v27, v135, v103, s[12:13]
	v_cndmask_b32_e64 v26, v134, v102, s[12:13]
	v_cndmask_b32_e64 v31, v121, v89, s[12:13]
	v_cndmask_b32_e64 v30, v120, v88, s[12:13]
	v_pk_add_f32 v[22:23], v[22:23], v[24:25]
	v_pk_add_f32 v[24:25], v[26:27], v[28:29]
	v_pk_add_f32 v[26:27], v[30:31], v[32:33]
	v_cndmask_b32_e64 v35, v123, v91, s[12:13]
	v_cndmask_b32_e64 v34, v122, v90, s[12:13]
	s_waitcnt lgkmcnt(2)
	v_pk_add_f32 v[28:29], v[34:35], v[36:37]
	v_cndmask_b32_e64 v5, v159, v109, s[12:13]
	v_cndmask_b32_e64 v4, v158, v108, s[12:13]
	v_cndmask_b32_e64 v9, v133, v101, s[12:13]
	v_cndmask_b32_e64 v8, v132, v100, s[12:13]
	v_cndmask_b32_e64 v15, v117, v85, s[12:13]
	v_cndmask_b32_e64 v14, v116, v84, s[12:13]
	v_pk_add_f32 v[4:5], v[4:5], v[6:7]
	v_pk_add_f32 v[6:7], v[8:9], v[12:13]
	v_pk_add_f32 v[8:9], v[14:15], v[16:17]
	v_cndmask_b32_e64 v19, v119, v87, s[12:13]
	v_cndmask_b32_e64 v18, v118, v86, s[12:13]
	s_waitcnt lgkmcnt(0)
; __device__ __forceinline__ float bflo(unsigned u) { return __uint_as_float(u << 16); }
; __device__ __forceinline__ float bfhi(unsigned u) { return __uint_as_float(u & 0xFFFF0000u); }
; __device__ __forceinline__ float siluf_(float x) { return x * __builtin_amdgcn_rcpf(1.f + __expf(-x)); }
; __device__ __forceinline__ void dsa_wave(const Params& p, int rank, char* sm) {
;     ...
;     for (int i = 0; i < 32; i++) { float lo = o[i], hi = o[32 + i]; float snd = b5 ? lo : hi; float kp = b5 ? hi : lo; o32[i] = kp + __shfl_xor(snd, 32); }
; #pragma unroll
;     for (int i = 0; i < 16; i++) { float lo = o32[i], hi = o32[16 + i]; float snd = b4 ? lo : hi; float kp = b4 ? hi : lo; o16[i] = kp + __shfl_xor(snd, 16); }
; #pragma unroll
;     for (int i = 0; i < 8; i++) { float lo = o16[i], hi = o16[8 + i]; float snd = b3 ? lo : hi; float kp = b3 ? hi : lo; o8[i] = kp + __shfl_xor(snd, 8); }
;     const float s_g0 = b4 ? (b3 ? ssum[0][3] : ssum[0][2]) : (b3 ? ssum[0][1] : ssum[0][0]);
;     const float s_g1 = b4 ? (b3 ? ssum[1][3] : ssum[1][2]) : (b3 ? ssum[1][1] : ssum[1][0]);
;     const float rinv = 1.f / (b5 ? s_g1 : s_g0);
;     const int hsel = (b5 ? 4 : 0) + (b4 ? 2 : 0) + (b3 ? 1 : 0);
;     const int col = hsel * 64 + dc * 8;
;     uint4 zz = *(const uint4*)(p.P + tq * PW + C_ATZ + col);
;     uint4 ov;
;     ov.x = pk2(o8[0] * rinv * siluf_(bflo(zz.x)), o8[1] * rinv * siluf_(bfhi(zz.x)));
;     ov.y = pk2(o8[2] * rinv * siluf_(bflo(zz.y)), o8[3] * rinv * siluf_(bfhi(zz.y)));
;     ov.z = pk2(o8[4] * rinv * siluf_(bflo(zz.z)), o8[5] * rinv * siluf_(bfhi(zz.z)));
;     ov.w = pk2(o8[6] * rinv * siluf_(bflo(zz.w)), o8[7] * rinv * siluf_(bfhi(zz.w)));
;     *(uint4*)(p.Y + tq * YW + Y_ATT + col) = ov;
	v_pk_add_f32 v[12:13], v[18:19], v[20:21]
	s_add_i32 s79, s79, 1
	v_add_u32_e32 v188, 0x800, v188
	s_cmp_eq_u32 s79, 8
	s_waitcnt vmcnt(0)
	v_lshlrev_b32_e32 v72, 16, v176
	v_and_b32_e32 v73, 0xffff0000, v176
	v_cndmask_b32_e64 v0, v54, v58, s[8:9]
	ds_bpermute_b32 v62, v70, v0
	v_cndmask_b32_e64 v0, v55, v59, s[8:9]
	ds_bpermute_b32 v63, v70, v0
	v_cndmask_b32_e64 v0, v56, v60, s[8:9]
	v_cndmask_b32_e64 v54, v58, v54, s[8:9]
	ds_bpermute_b32 v58, v70, v0
	v_cndmask_b32_e64 v0, v57, v61, s[8:9]
	v_cndmask_b32_e64 v55, v59, v55, s[8:9]
	ds_bpermute_b32 v59, v70, v0
	v_cndmask_b32_e64 v57, v61, v57, s[8:9]
	v_cndmask_b32_e64 v56, v60, v56, s[8:9]
	s_waitcnt lgkmcnt(2)
	v_pk_add_f32 v[54:55], v[54:55], v[62:63]
	s_waitcnt lgkmcnt(0)
	v_pk_add_f32 v[56:57], v[56:57], v[58:59]
	s_nop 0
	v_cndmask_b32_e64 v0, v54, v56, s[10:11]
	ds_bpermute_b32 v58, v11, v0
	v_cndmask_b32_e64 v0, v55, v57, s[10:11]
	ds_bpermute_b32 v59, v11, v0
	v_mul_f32_e32 v0, 0xbfb8aa3b, v72
	v_exp_f32_e32 v0, v0
	v_cndmask_b32_e64 v54, v56, v54, s[10:11]
	v_cndmask_b32_e64 v55, v57, v55, s[10:11]
	s_waitcnt lgkmcnt(0)
	v_pk_add_f32 v[54:55], v[54:55], v[58:59]
	v_add_f32_e32 v0, 1.0, v0
	v_rcp_f32_e32 v56, v0
	v_mul_f32_e32 v0, 0xbfb8aa3b, v73
	v_exp_f32_e32 v0, v0
	v_pk_mul_f32 v[54:55], v[10:11], v[54:55] op_sel_hi:[0,1]
	v_add_f32_e32 v0, 1.0, v0
	v_rcp_f32_e32 v57, v0
	s_nop 0
	v_pk_mul_f32 v[56:57], v[56:57], v[72:73]
	s_nop 0
	v_pk_mul_f32 v[54:55], v[54:55], v[56:57]
	s_nop 0
	v_cvt_pk_bf16_f32 v0, v54, v55
	v_lshlrev_b32_e32 v54, 16, v177
	v_and_b32_e32 v55, 0xffff0000, v177
	v_cndmask_b32_e64 v1, v38, v42, s[8:9]
	ds_bpermute_b32 v46, v70, v1
	v_cndmask_b32_e64 v1, v39, v43, s[8:9]
	ds_bpermute_b32 v47, v70, v1
	v_cndmask_b32_e64 v1, v40, v44, s[8:9]
	v_cndmask_b32_e64 v38, v42, v38, s[8:9]
	ds_bpermute_b32 v42, v70, v1
	v_cndmask_b32_e64 v1, v41, v45, s[8:9]
	v_cndmask_b32_e64 v39, v43, v39, s[8:9]
	ds_bpermute_b32 v43, v70, v1
	v_cndmask_b32_e64 v41, v45, v41, s[8:9]
	v_cndmask_b32_e64 v40, v44, v40, s[8:9]
	s_waitcnt lgkmcnt(2)
	v_pk_add_f32 v[38:39], v[38:39], v[46:47]
	s_waitcnt lgkmcnt(0)
	v_pk_add_f32 v[40:41], v[40:41], v[42:43]
	s_nop 0
	v_cndmask_b32_e64 v1, v38, v40, s[10:11]
	ds_bpermute_b32 v42, v11, v1
	v_cndmask_b32_e64 v1, v39, v41, s[10:11]
	ds_bpermute_b32 v43, v11, v1
	v_mul_f32_e32 v1, 0xbfb8aa3b, v54
	v_exp_f32_e32 v1, v1
	v_cndmask_b32_e64 v38, v40, v38, s[10:11]
	v_cndmask_b32_e64 v39, v41, v39, s[10:11]
	s_waitcnt lgkmcnt(0)
	v_pk_add_f32 v[38:39], v[38:39], v[42:43]
	v_add_f32_e32 v1, 1.0, v1
	v_rcp_f32_e32 v40, v1
	v_mul_f32_e32 v1, 0xbfb8aa3b, v55
	v_exp_f32_e32 v1, v1
	v_pk_mul_f32 v[38:39], v[10:11], v[38:39] op_sel_hi:[0,1]
	v_add_f32_e32 v1, 1.0, v1
	v_rcp_f32_e32 v41, v1
	s_nop 0
	v_pk_mul_f32 v[40:41], v[40:41], v[54:55]
	s_nop 0
	v_pk_mul_f32 v[38:39], v[38:39], v[40:41]
	s_nop 0
	v_cvt_pk_bf16_f32 v1, v38, v39
	v_lshlrev_b32_e32 v38, 16, v178
	v_and_b32_e32 v39, 0xffff0000, v178
	v_cndmask_b32_e64 v2, v22, v26, s[8:9]
	ds_bpermute_b32 v30, v70, v2
	v_cndmask_b32_e64 v2, v23, v27, s[8:9]
	ds_bpermute_b32 v31, v70, v2
	v_cndmask_b32_e64 v2, v24, v28, s[8:9]
	v_cndmask_b32_e64 v22, v26, v22, s[8:9]
	ds_bpermute_b32 v26, v70, v2
	v_cndmask_b32_e64 v2, v25, v29, s[8:9]
	v_cndmask_b32_e64 v23, v27, v23, s[8:9]
	ds_bpermute_b32 v27, v70, v2
	v_cndmask_b32_e64 v25, v29, v25, s[8:9]
	v_cndmask_b32_e64 v24, v28, v24, s[8:9]
	s_waitcnt lgkmcnt(2)
	v_pk_add_f32 v[22:23], v[22:23], v[30:31]
	s_waitcnt lgkmcnt(0)
	v_pk_add_f32 v[24:25], v[24:25], v[26:27]
	s_nop 0
	v_cndmask_b32_e64 v2, v22, v24, s[10:11]
	ds_bpermute_b32 v26, v11, v2
	v_cndmask_b32_e64 v2, v23, v25, s[10:11]
	ds_bpermute_b32 v27, v11, v2
	v_mul_f32_e32 v2, 0xbfb8aa3b, v38
	v_exp_f32_e32 v2, v2
	v_cndmask_b32_e64 v22, v24, v22, s[10:11]
	v_cndmask_b32_e64 v23, v25, v23, s[10:11]
	s_waitcnt lgkmcnt(0)
	v_pk_add_f32 v[22:23], v[22:23], v[26:27]
	v_add_f32_e32 v2, 1.0, v2
	v_rcp_f32_e32 v24, v2
	v_mul_f32_e32 v2, 0xbfb8aa3b, v39
	v_exp_f32_e32 v2, v2
	v_pk_mul_f32 v[22:23], v[10:11], v[22:23] op_sel_hi:[0,1]
	v_add_f32_e32 v2, 1.0, v2
	v_rcp_f32_e32 v25, v2
	s_nop 0
	v_pk_mul_f32 v[24:25], v[24:25], v[38:39]
	s_nop 0
	v_pk_mul_f32 v[22:23], v[22:23], v[24:25]
	s_nop 0
	v_cvt_pk_bf16_f32 v2, v22, v23
	v_lshlrev_b32_e32 v22, 16, v179
	v_and_b32_e32 v23, 0xffff0000, v179
	v_cndmask_b32_e64 v3, v4, v8, s[8:9]
	ds_bpermute_b32 v14, v70, v3
	v_cndmask_b32_e64 v3, v5, v9, s[8:9]
	ds_bpermute_b32 v15, v70, v3
	v_cndmask_b32_e64 v3, v6, v12, s[8:9]
	v_cndmask_b32_e64 v4, v8, v4, s[8:9]
	ds_bpermute_b32 v8, v70, v3
	v_cndmask_b32_e64 v3, v7, v13, s[8:9]
	v_cndmask_b32_e64 v5, v9, v5, s[8:9]
	ds_bpermute_b32 v9, v70, v3
	v_cndmask_b32_e64 v7, v13, v7, s[8:9]
	v_cndmask_b32_e64 v6, v12, v6, s[8:9]
	s_waitcnt lgkmcnt(2)
	v_pk_add_f32 v[4:5], v[4:5], v[14:15]
	s_waitcnt lgkmcnt(0)
	v_pk_add_f32 v[6:7], v[6:7], v[8:9]
	s_nop 0
	v_cndmask_b32_e64 v3, v4, v6, s[10:11]
	ds_bpermute_b32 v8, v11, v3
	v_cndmask_b32_e64 v3, v5, v7, s[10:11]
	ds_bpermute_b32 v9, v11, v3
	v_mul_f32_e32 v3, 0xbfb8aa3b, v22
	v_exp_f32_e32 v3, v3
	v_cndmask_b32_e64 v4, v6, v4, s[10:11]
	v_cndmask_b32_e64 v5, v7, v5, s[10:11]
	s_waitcnt lgkmcnt(0)
	v_pk_add_f32 v[4:5], v[4:5], v[8:9]
	v_add_f32_e32 v3, 1.0, v3
	v_rcp_f32_e32 v6, v3
	v_mul_f32_e32 v3, 0xbfb8aa3b, v23
	v_exp_f32_e32 v3, v3
	v_pk_mul_f32 v[4:5], v[10:11], v[4:5] op_sel_hi:[0,1]
	v_add_f32_e32 v3, 1.0, v3
	v_rcp_f32_e32 v7, v3
	s_nop 0
	v_pk_mul_f32 v[6:7], v[6:7], v[22:23]
	s_nop 0
	v_pk_mul_f32 v[4:5], v[4:5], v[6:7]
	s_nop 0
	v_cvt_pk_bf16_f32 v3, v4, v5
	v_mad_u64_u32 v[4:5], s[0:1], v189, s97, v[150:151]
	v_mov_b32_e32 v6, v5
	v_mad_u64_u32 v[6:7], s[0:1], v149, s97, v[6:7]
	v_mov_b32_e32 v5, v6
	global_store_dwordx4 v[4:5], v[0:3], off offset:1024
	s_cbranch_scc1 .LBB0_532

; __device__ __forceinline__ float ozero() { float z = 0.f; asm volatile("" : "+v"(z)); return z; }
; __device__ __forceinline__ void dsa_wave(const Params& p, int rank, char* sm) {
;     ...
;     float o[64];
; #pragma unroll
;     for (int i = 0; i < 64; i++) o[i] = ozero();
;     const int ksg = lane >> 3, dc = lane & 7;
; #pragma unroll 8
;     for (int stp = 0; stp < 32; stp++) {
;       const int slot = stp * 8 + ksg;
;       const int key = (slot < n) ? (16383 - (int)(sel[slot] & 0x3FFFu)) : 0;
;       uint4 pp = *(const uint4*)(Pb + slot * 8);
;       const bf* vp = p.KVC + (tokb + key) * 256 + 128 + dc * 8;
.LBB0_1534:
	s_or_b64 exec, exec, s[0:1]
	v_lshl_add_u64 v[180:181], v[142:143], 0, v[152:153]
	global_load_dwordx4 v[176:179], v[180:181], off offset:3584
	s_mov_b32 s16, 0
	v_mov_b32_e32 v114, v145
	v_mov_b32_e32 v115, v145
	v_mov_b32_e32 v112, v145
	v_mov_b32_e32 v113, v145
	v_mov_b32_e32 v110, v145
	v_mov_b32_e32 v111, v145
	v_mov_b32_e32 v108, v145
	v_mov_b32_e32 v109, v145
	v_mov_b32_e32 v106, v145
	v_mov_b32_e32 v107, v145
	v_mov_b32_e32 v104, v145
	v_mov_b32_e32 v105, v145
	v_mov_b32_e32 v102, v145
	v_mov_b32_e32 v103, v145
	v_mov_b32_e32 v100, v145
	v_mov_b32_e32 v101, v145
	v_mov_b32_e32 v96, v145
	v_mov_b32_e32 v97, v145
	v_mov_b32_e32 v92, v145
	v_mov_b32_e32 v93, v145
	v_mov_b32_e32 v88, v145
	v_mov_b32_e32 v89, v145
	v_mov_b32_e32 v84, v145
	v_mov_b32_e32 v85, v145
	v_mov_b32_e32 v98, v145
	v_mov_b32_e32 v99, v145
	v_mov_b32_e32 v94, v145
	v_mov_b32_e32 v95, v145
	v_mov_b32_e32 v90, v145
	v_mov_b32_e32 v91, v145
	v_mov_b32_e32 v86, v145
	v_mov_b32_e32 v87, v145
	v_mov_b32_e32 v164, v145
	v_mov_b32_e32 v165, v145
	v_mov_b32_e32 v162, v145
	v_mov_b32_e32 v163, v145
	v_mov_b32_e32 v160, v145
	v_mov_b32_e32 v161, v145
	v_mov_b32_e32 v158, v145
	v_mov_b32_e32 v159, v145
	v_mov_b32_e32 v156, v145
	v_mov_b32_e32 v157, v145
	v_mov_b32_e32 v154, v145
	v_mov_b32_e32 v155, v145
	v_mov_b32_e32 v134, v145
	v_mov_b32_e32 v135, v145
	v_mov_b32_e32 v132, v145
	v_mov_b32_e32 v133, v145
	v_mov_b32_e32 v128, v145
	v_mov_b32_e32 v129, v145
	v_mov_b32_e32 v124, v145
	v_mov_b32_e32 v125, v145
	v_mov_b32_e32 v120, v145
	v_mov_b32_e32 v121, v145
	v_mov_b32_e32 v116, v145
	v_mov_b32_e32 v117, v145
	v_mov_b32_e32 v130, v145
	v_mov_b32_e32 v131, v145
	v_mov_b32_e32 v126, v145
	v_mov_b32_e32 v127, v145
	v_mov_b32_e32 v122, v145
	v_mov_b32_e32 v123, v145
	v_mov_b32_e32 v118, v145
	v_mov_b32_e32 v119, v145
	v_mov_b32_e32 v190, v188
	v_mov_b32_e32 v191, v187
	s_branch .LBB0_1536
